# attention unit loop: loop-top vmcnt waits (which on the back edge only waited for the previous unit's stores) replaced by one drain before the loop
# baseline (speedup 1.0000x reference)
.LBB0_313:
	s_and_b64 vcc, exec, s[8:9]
	s_cbranch_vccnz .LBB0_438
	v_and_b32_e32 v3, 64, v209
	v_xor_b32_e32 v2, 1, v209
	v_add_u32_e32 v3, 64, v3
	v_cmp_lt_i32_e32 vcc, v2, v3
	v_lshlrev_b32_e32 v0, 2, v73
	v_readlane_b32 s58, v253, 8
	v_cndmask_b32_e32 v2, v209, v2, vcc
	v_lshlrev_b32_e32 v174, 2, v2
	v_xor_b32_e32 v2, 2, v209
	v_cmp_lt_i32_e32 vcc, v2, v3
	v_readlane_b32 s12, v253, 23
	v_add_u32_e32 v173, s58, v0
	v_cndmask_b32_e32 v2, v209, v2, vcc
	v_lshlrev_b32_e32 v175, 2, v2
	v_xor_b32_e32 v2, 4, v209
	v_and_b32_e32 v0, 0x1fc, v0
	s_and_b64 s[8:9], s[92:93], exec
	v_readlane_b32 s13, v253, 24
	v_cmp_lt_i32_e32 vcc, v2, v3
	v_add_u32_e32 v69, 0, v0
	v_xor_b32_e32 v0, 16, v209
	s_cselect_b32 s0, 5, 3
	s_and_b64 s[8:9], s[12:13], exec
	v_cndmask_b32_e32 v2, v209, v2, vcc
	v_cmp_lt_i32_e32 vcc, v0, v3
	s_cselect_b32 s47, 7, s0
	s_add_i32 s56, s56, -1
	s_lshl_b32 s24, s28, 4
	v_cndmask_b32_e32 v0, v209, v0, vcc
	s_and_b64 s[8:9], s[92:93], exec
	v_lshlrev_b32_e32 v177, 2, v0
	v_xor_b32_e32 v0, 32, v209
	s_cselect_b32 s0, 2, 4
	s_and_b64 s[8:9], s[12:13], exec
	v_cmp_lt_i32_e32 vcc, v0, v3
	v_add_u32_e32 v3, 0x400, v73
	s_cselect_b32 s57, 0, s0
	v_cndmask_b32_e32 v0, v209, v0, vcc
	s_and_b64 s[8:9], s[92:93], exec
	v_ashrrev_i32_e32 v180, 3, v3
	v_add_u32_e32 v3, 0x600, v73
	v_lshlrev_b32_e32 v178, 2, v0
	s_cselect_b32 s0, 12, 10
	s_and_b64 s[8:9], s[12:13], exec
	v_add_u32_e32 v0, 0x200, v73
	v_ashrrev_i32_e32 v181, 3, v3
	v_lshlrev_b32_e32 v3, 1, v73
	s_cselect_b32 s99, 14, s0
	v_ashrrev_i32_e32 v179, 3, v0
	v_and_b32_e32 v182, 0xfe, v3
	v_ashrrev_i32_e32 v3, 4, v73
	v_ashrrev_i32_e32 v0, 4, v0
	s_ashr_i32 s0, s24, 31
	v_and_b32_e32 v124, -8, v3
	v_and_b32_e32 v126, -8, v0
	v_mov_b32_e32 v121, s0
	s_movk_i32 s0, 0x210
	v_lshlrev_b32_e32 v128, 2, v74
	v_mul_lo_u32 v78, v124, s0
	v_mul_lo_u32 v79, v126, s0
	s_add_i32 s29, s28, 2
	s_add_i32 s35, s28, 4
	s_add_i32 s34, s28, 6
	s_add_i32 s0, s28, 8
	v_mov_b32_e32 v71, v1
	v_sub_u32_e32 v0, v72, v128
	s_add_i32 s40, s24, 16
	s_lshl_b32 s41, s29, 4
	s_add_i32 s42, s24, 48
	s_lshl_b32 s43, s35, 4
	s_add_i32 s49, s24, 0x50
	s_lshl_b32 s52, s34, 4
	s_add_i32 s48, s24, 0x70
	s_lshl_b32 s53, s0, 4
	v_or_b32_e32 v120, s24, v72
	v_lshl_add_u64 v[122:123], s[10:11], 0, v[70:71]
	v_add_u32_e32 v70, 0x80, v0
	s_movk_i32 s8, 0x90
	v_or_b32_e32 v81, s40, v72
	v_or_b32_e32 v82, s41, v72
	v_or_b32_e32 v83, s42, v72
	v_or_b32_e32 v84, s43, v72
	v_or_b32_e32 v85, s49, v72
	v_or_b32_e32 v86, s52, v72
	v_or_b32_e32 v87, s48, v72
	v_or_b32_e32 v88, s53, v72
	s_movk_i32 s55, 0x81
	v_lshl_add_u32 v3, v74, 4, 0
	v_cmp_eq_u32_e32 vcc, 0, v74
	v_mul_lo_u32 v74, v129, s8
	v_mul_lo_u32 v75, v179, s8
	v_mul_lo_u32 v76, v180, s8
	v_mul_lo_u32 v77, v181, s8
	v_mul_lo_u32 v80, v120, s8
	v_mul_lo_u32 v81, v81, s8
	v_mul_lo_u32 v82, v82, s8
	v_mul_lo_u32 v83, v83, s8
	v_mul_lo_u32 v84, v84, s8
	v_mul_lo_u32 v85, v85, s8
	v_mul_lo_u32 v86, v86, s8
	v_mul_lo_u32 v87, v87, s8
	v_mul_lo_u32 v88, v88, s8
	v_cmp_gt_u32_e64 s[8:9], s55, v70
	v_lshl_add_u32 v183, v70, 2, s58
	v_add_u32_e32 v70, 0x7f, v0
	v_cmp_gt_u32_e64 s[10:11], s55, v70
	v_lshl_add_u32 v184, v70, 2, s58
	v_add_u32_e32 v70, 0x7e, v0
	v_cmp_gt_u32_e64 s[12:13], s55, v70
	v_lshl_add_u32 v185, v70, 2, s58
	v_add_u32_e32 v70, 0x7d, v0
	v_lshl_add_u32 v187, v0, 2, s58
	v_cmp_lt_i32_e64 s[16:17], -1, v0
	v_cmp_lt_i32_e64 s[18:19], 0, v0
	v_cmp_lt_i32_e64 s[20:21], 1, v0
	v_cmp_lt_i32_e64 s[22:23], 2, v0
	v_or_b32_e32 v0, s24, v128
	s_movk_i32 s54, 0x7f
	s_and_b64 s[38:39], s[88:89], vcc
	v_cmp_gt_u32_e64 s[14:15], s55, v70
	v_lshl_add_u32 v186, v70, 2, s58
	v_cmp_lt_i32_e32 vcc, s54, v0
	v_or_b32_e32 v70, 1, v128
	s_and_b64 s[24:25], s[8:9], vcc
	v_sub_u32_e32 v89, v72, v70
	v_writelane_b32 v254, s24, 39
	v_add_u32_e32 v90, 0x80, v89
	s_movk_i32 s59, 0x7e
	v_lshl_add_u32 v191, v89, 2, s58
	v_or_b32_e32 v89, 2, v128
	v_writelane_b32 v254, s25, 40
	v_cmp_gt_u32_e32 vcc, s55, v90
	v_cmp_lt_i32_e64 s[24:25], s59, v0
	v_sub_u32_e32 v90, v72, v89
	s_and_b64 s[24:25], vcc, s[24:25]
	v_add_u32_e32 v91, 0x80, v90
	v_writelane_b32 v254, s24, 41
	v_cmp_gt_u32_e32 vcc, s55, v91
	v_or_b32_e32 v91, 2, v0
	v_writelane_b32 v254, s25, 42
	v_cmp_lt_i32_e64 s[24:25], s54, v91
	v_lshl_add_u32 v192, v90, 2, s58
	v_or_b32_e32 v90, 3, v128
	s_and_b64 s[24:25], vcc, s[24:25]
	v_sub_u32_e32 v91, v72, v90
	v_writelane_b32 v254, s24, 35
	v_add_u32_e32 v92, 0x80, v91
	v_or_b32_e32 v0, 3, v0
	v_writelane_b32 v254, s25, 36
	v_cmp_gt_u32_e32 vcc, s55, v92
	v_cmp_lt_i32_e64 s[24:25], s54, v0
	s_and_b64 s[24:25], vcc, s[24:25]
	v_or_b32_e32 v0, s40, v128
	v_writelane_b32 v254, s24, 25
	v_lshlrev_b32_e32 v176, 2, v2
	v_lshlrev_b32_e32 v2, 4, v73
	v_writelane_b32 v254, s25, 26
	v_or_b32_e32 v73, -16, v73
	v_cmp_lt_i32_e64 s[24:25], s54, v0
	v_lshl_add_u32 v193, v91, 2, s58
	v_sub_u32_e32 v91, v73, v128
	v_writelane_b32 v254, s24, 33
	v_lshl_add_u32 v194, v91, 2, s58
	v_sub_u32_e32 v91, v73, v70
	v_writelane_b32 v254, s25, 34
	v_cmp_lt_i32_e64 s[24:25], s59, v0
	v_lshl_add_u32 v195, v91, 2, s58
	v_or_b32_e32 v91, 2, v0
	v_writelane_b32 v254, s24, 27
	v_or_b32_e32 v0, 3, v0
	v_or_b32_e32 v93, 0xffffff80, v72
	v_writelane_b32 v254, s25, 28
	v_cmp_lt_i32_e64 s[24:25], s54, v91
	v_sub_u32_e32 v91, v73, v89
	v_lshl_add_u32 v196, v91, 2, s58
	v_writelane_b32 v254, s24, 43
	v_sub_u32_e32 v94, v93, v128
	v_add_u32_e32 v95, 0x80, v94
	v_writelane_b32 v254, s25, 44
	v_cmp_lt_i32_e64 s[24:25], s54, v0
	v_sub_u32_e32 v0, v73, v90
	v_lshl_add_u32 v197, v0, 2, s58
	v_writelane_b32 v254, s24, 37
	v_or_b32_e32 v0, s41, v128
	v_or_b32_e32 v73, 0xffffffe0, v72
	v_writelane_b32 v254, s25, 38
	v_cmp_lt_i32_e64 s[24:25], s54, v0
	v_sub_u32_e32 v91, v73, v128
	v_lshl_add_u32 v198, v91, 2, s58
	v_writelane_b32 v254, s24, 29
	v_sub_u32_e32 v91, v73, v70
	v_lshl_add_u32 v200, v91, 2, s58
	v_writelane_b32 v254, s25, 30
	v_cmp_lt_i32_e64 s[24:25], s59, v0
	v_or_b32_e32 v91, 2, v0
	v_or_b32_e32 v0, 3, v0
	v_writelane_b32 v254, s24, 31
	v_or_b32_e32 v92, s53, v128
	v_cmp_gt_u32_e32 vcc, s55, v95
	v_writelane_b32 v254, s25, 32
	v_cmp_lt_i32_e64 s[24:25], s54, v91
	v_sub_u32_e32 v91, v73, v89
	v_lshl_add_u32 v201, v91, 2, s58
	v_writelane_b32 v254, s24, 45
	v_sub_u32_e32 v95, v93, v70
	v_cmp_lt_i32_e64 s[64:65], s54, v92
	v_writelane_b32 v254, s25, 46
	v_cmp_lt_i32_e64 s[24:25], s54, v0
	v_sub_u32_e32 v0, v73, v90
	v_lshl_add_u32 v202, v0, 2, s58
	v_writelane_b32 v254, s24, 47
	v_or_b32_e32 v0, s42, v128
	v_or_b32_e32 v73, 0xffffffd0, v72
	v_writelane_b32 v254, s25, 48
	v_cmp_lt_i32_e64 s[24:25], s54, v0
	v_sub_u32_e32 v91, v73, v128
	v_lshl_add_u32 v203, v91, 2, s58
	v_writelane_b32 v254, s24, 49
	v_sub_u32_e32 v91, v73, v70
	v_lshl_add_u32 v210, v91, 2, s58
	v_writelane_b32 v254, s25, 50
	v_cmp_lt_i32_e64 s[24:25], s59, v0
	v_or_b32_e32 v91, 2, v0
	v_or_b32_e32 v0, 3, v0
	v_writelane_b32 v254, s24, 51
	v_add_u32_e32 v96, 0x80, v95
	s_and_b64 s[40:41], vcc, s[64:65]
	v_writelane_b32 v254, s25, 52
	v_cmp_lt_i32_e64 s[24:25], s54, v91
	v_sub_u32_e32 v91, v73, v89
	v_lshl_add_u32 v211, v91, 2, s58
	v_writelane_b32 v254, s24, 53
	v_cmp_gt_u32_e32 vcc, s55, v96
	v_sub_u32_e32 v96, v93, v89
	v_writelane_b32 v254, s25, 54
	v_cmp_lt_i32_e64 s[24:25], s54, v0
	v_sub_u32_e32 v0, v73, v90
	v_lshl_add_u32 v212, v0, 2, s58
	v_writelane_b32 v254, s24, 55
	v_or_b32_e32 v0, s43, v128
	v_or_b32_e32 v73, 0xffffffc0, v72
	v_writelane_b32 v254, s25, 56
	v_cmp_lt_i32_e64 s[24:25], s54, v0
	v_sub_u32_e32 v91, v73, v128
	v_lshl_add_u32 v213, v91, 2, s58
	v_writelane_b32 v254, s24, 57
	v_sub_u32_e32 v91, v73, v70
	v_lshl_add_u32 v214, v91, 2, s58
	v_writelane_b32 v254, s25, 58
	v_cmp_lt_i32_e64 s[24:25], s59, v0
	v_or_b32_e32 v91, 2, v0
	v_or_b32_e32 v0, 3, v0
	v_writelane_b32 v254, s24, 59
	v_cmp_lt_i32_e64 s[64:65], s59, v92
	v_add_u32_e32 v97, 0x80, v96
	v_writelane_b32 v254, s25, 60
	v_cmp_lt_i32_e64 s[24:25], s54, v91
	v_sub_u32_e32 v91, v73, v89
	v_lshl_add_u32 v215, v91, 2, s58
	v_writelane_b32 v254, s24, 61
	s_and_b64 s[42:43], vcc, s[64:65]
	v_cmp_gt_u32_e32 vcc, s55, v97
	v_writelane_b32 v254, s25, 62
	v_cmp_lt_i32_e64 s[24:25], s54, v0
	v_sub_u32_e32 v0, v73, v90
	v_or_b32_e32 v73, 0xffffffb0, v72
	v_sub_u32_e32 v91, v73, v128
	v_or_b32_e32 v97, 2, v92
	v_sub_u32_e32 v93, v93, v90
	v_writelane_b32 v254, s24, 63
	v_lshl_add_u32 v216, v0, 2, s58
	v_or_b32_e32 v0, s49, v128
	v_lshl_add_u32 v217, v91, 2, s58
	v_sub_u32_e32 v91, v73, v70
	v_cmp_lt_i32_e64 s[64:65], s54, v97
	v_add_u32_e32 v97, 0x80, v93
	v_or_b32_e32 v92, 3, v92
	v_writelane_b32 v255, s25, 0
	v_cmp_lt_i32_e64 s[24:25], s54, v0
	v_cmp_lt_i32_e64 s[60:61], s59, v0
	v_lshl_add_u32 v218, v91, 2, s58
	v_or_b32_e32 v91, 2, v0
	v_or_b32_e32 v0, 3, v0
	s_and_b64 s[88:89], vcc, s[64:65]
	v_cmp_gt_u32_e32 vcc, s55, v97
	v_cmp_lt_i32_e64 s[64:65], s54, v92
	s_and_b64 s[92:93], vcc, s[64:65]
	v_cmp_lt_i32_e64 s[64:65], s54, v0
	v_sub_u32_e32 v0, v73, v90
	v_cmp_lt_i32_e64 s[62:63], s54, v91
	v_sub_u32_e32 v91, v73, v89
	v_lshl_add_u32 v220, v0, 2, s58
	v_or_b32_e32 v0, 0xffffffa0, v72
	v_lshl_add_u32 v219, v91, 2, s58
	v_or_b32_e32 v91, s52, v128
	v_sub_u32_e32 v99, v0, v70
	v_lshl_add_u32 v222, v99, 2, s58
	v_or_b32_e32 v99, 2, v91
	v_sub_u32_e32 v97, v0, v128
	v_cmp_lt_i32_e64 s[70:71], s54, v99
	v_sub_u32_e32 v99, v0, v89
	v_sub_u32_e32 v0, v0, v90
	v_writelane_b32 v255, s24, 1
	v_lshl_add_u32 v224, v0, 2, s58
	v_or_b32_e32 v0, 0xffffff90, v72
	v_and_b32_e32 v2, 0x70, v2
	v_sub_u32_e32 v71, v3, v68
	v_writelane_b32 v255, s25, 2
	v_or_b32_e32 v73, s48, v128
	v_lshl_add_u32 v223, v99, 2, s58
	v_sub_u32_e32 v99, v0, v128
	v_sub_u32_e32 v70, v0, v70
	v_sub_u32_e32 v89, v0, v89
	v_sub_u32_e32 v0, v0, v90
	v_readlane_b32 s24, v254, 12
	v_add_u32_e32 v2, 0, v2
	v_lshl_add_u32 v92, s28, 5, v71
	v_cmp_lt_i32_e64 s[66:67], s54, v91
	v_lshl_add_u32 v221, v97, 2, s58
	v_lshl_add_u32 v97, s29, 5, v71
	v_lshl_add_u32 v98, s35, 5, v71
	v_cmp_lt_i32_e64 s[68:69], s59, v91
	v_lshl_add_u32 v100, s34, 5, v71
	v_lshl_add_u32 v71, s0, 5, v71
	v_or_b32_e32 v91, 3, v91
	v_lshl_add_u32 v226, v70, 2, s58
	v_or_b32_e32 v70, 2, v73
	v_lshl_add_u32 v227, v89, 2, s58
	v_or_b32_e32 v89, 3, v73
	v_lshl_add_u32 v228, v0, 2, s58
	v_mul_u32_u24_e32 v72, 0x210, v72
	v_lshlrev_b32_e32 v0, 1, v68
	v_readlane_b32 s25, v254, 13
	v_ashrrev_i32_e32 v125, 31, v124
	v_ashrrev_i32_e32 v127, 31, v126
	v_add_u32_e32 v188, -4, v187
	v_add_u32_e32 v189, -8, v187
	v_add_u32_e32 v190, -12, v187
	v_lshl_add_u32 v225, v99, 2, s58
	v_lshl_add_u32 v229, v94, 2, s58
	v_lshl_add_u32 v230, v95, 2, s58
	v_lshl_add_u32 v231, v96, 2, s58
	v_lshl_add_u32 v232, v93, 2, s58
	v_lshl_add_u64 v[132:133], s[24:25], 0, v[0:1]
	v_add_u32_e32 v233, v2, v74
	v_add_u32_e32 v234, v2, v75
	v_add_u32_e32 v235, v2, v76
	v_add_u32_e32 v236, v2, v77
	v_add_u32_e32 v237, v69, v78
	v_add_u32_e32 v238, v69, v79
	v_add_u32_e32 v239, v3, v80
	v_add_u32_e32 v240, v3, v81
	v_add_u32_e32 v241, v3, v82
	v_add_u32_e32 v242, v3, v83
	v_add_u32_e32 v243, v3, v84
	v_add_u32_e32 v244, v3, v85
	v_add_u32_e32 v245, v3, v86
	v_add_u32_e32 v246, v3, v87
	v_add_u32_e32 v247, v3, v88
	v_add_u32_e32 v248, v92, v72
	v_add_u32_e32 v249, v97, v72
	v_add_u32_e32 v250, v98, v72
	v_add_u32_e32 v251, v100, v72
	v_add_u32_e32 v206, v71, v72
	v_readlane_b32 s58, v252, 47
	v_cmp_lt_i32_e64 s[72:73], s54, v91
	v_cmp_lt_i32_e64 s[74:75], s54, v73
	v_cmp_lt_i32_e64 s[76:77], s59, v73
	v_cmp_lt_i32_e64 s[78:79], s54, v70
	v_cmp_lt_i32_e64 s[80:81], s54, v89
	s_waitcnt vmcnt(0)
	s_branch .LBB0_316

.LBB0_316:
	s_barrier
	s_and_saveexec_b64 s[24:25], s[6:7]
	s_cbranch_execz .LBB0_318
	v_mul_f32_e32 v0, 0x3fb8aa3b, v172
	ds_write_b32 v173, v0
.LBB0_318:
	s_or_b64 exec, exec, s[24:25]
	v_lshlrev_b32_e32 v78, 16, v32
	v_and_b32_e32 v79, 0xffff0000, v32
	v_lshlrev_b32_e32 v74, 16, v33
	v_and_b32_e32 v75, 0xffff0000, v33
	v_pk_mul_f32 v[80:81], v[78:79], v[78:79]
	v_pk_mul_f32 v[76:77], v[74:75], v[74:75]
	v_add_f32_e32 v0, v80, v81
	v_lshlrev_b32_e32 v70, 16, v34
	v_and_b32_e32 v71, 0xffff0000, v34
	v_add_f32_e32 v0, v76, v0
	v_pk_mul_f32 v[72:73], v[70:71], v[70:71]
	v_add_f32_e32 v0, v77, v0
	v_lshlrev_b32_e32 v2, 16, v35
	v_and_b32_e32 v3, 0xffff0000, v35
	v_add_f32_e32 v0, v72, v0
	v_pk_mul_f32 v[68:69], v[2:3], v[2:3]
	v_add_f32_e32 v0, v73, v0
	v_add_f32_e32 v0, v68, v0
	v_add_f32_e32 v0, v69, v0
	ds_bpermute_b32 v68, v174, v0
	v_lshlrev_b32_e32 v86, 16, v28
	v_and_b32_e32 v87, 0xffff0000, v28
	v_lshlrev_b32_e32 v102, 16, v36
	v_and_b32_e32 v103, 0xffff0000, v36
	s_waitcnt lgkmcnt(0)
	v_add_f32_e32 v0, v0, v68
	ds_bpermute_b32 v68, v175, v0
	v_lshlrev_b32_e32 v82, 16, v29
	v_and_b32_e32 v83, 0xffff0000, v29
	v_pk_mul_f32 v[88:89], v[86:87], v[86:87]
	v_lshlrev_b32_e32 v98, 16, v37
	s_waitcnt lgkmcnt(0)
	v_add_f32_e32 v0, v0, v68
	ds_bpermute_b32 v68, v176, v0
	v_and_b32_e32 v99, 0xffff0000, v37
	v_pk_mul_f32 v[104:105], v[102:103], v[102:103]
	v_pk_mul_f32 v[84:85], v[82:83], v[82:83]
	v_pk_mul_f32 v[100:101], v[98:99], v[98:99]
	v_mov_b32_e32 v106, v104
	v_mov_b32_e32 v107, v88
	v_mov_b32_e32 v88, v105
	s_waitcnt lgkmcnt(0)
	v_add_f32_e32 v0, v0, v68
	v_lshlrev_b32_e32 v76, 16, v30
	v_and_b32_e32 v77, 0xffff0000, v30
	v_lshlrev_b32_e32 v94, 16, v38
	v_and_b32_e32 v95, 0xffff0000, v38
	v_pk_add_f32 v[88:89], v[106:107], v[88:89]
	v_mov_b32_e32 v104, v100
	v_mov_b32_e32 v105, v84
	v_fmamk_f32 v0, v0, 0x3c800000, v205
	v_pk_mul_f32 v[80:81], v[76:77], v[76:77]
	v_pk_mul_f32 v[96:97], v[94:95], v[94:95]
	v_pk_add_f32 v[88:89], v[104:105], v[88:89]
	v_mov_b32_e32 v84, v101
	v_lshlrev_b32_e32 v72, 16, v31
	v_mul_f32_e32 v68, 0x4b800000, v0
	v_cmp_gt_f32_e32 vcc, s83, v0
	v_and_b32_e32 v73, 0xffff0000, v31
	v_lshlrev_b32_e32 v90, 16, v39
	v_and_b32_e32 v91, 0xffff0000, v39
	v_pk_add_f32 v[84:85], v[84:85], v[88:89]
	v_mov_b32_e32 v88, v96
	v_mov_b32_e32 v89, v80
	v_cndmask_b32_e32 v0, v0, v68, vcc
	v_pk_mul_f32 v[68:69], v[72:73], v[72:73]
	v_pk_mul_f32 v[92:93], v[90:91], v[90:91]
	v_pk_add_f32 v[84:85], v[88:89], v[84:85]
	v_mov_b32_e32 v80, v97
	v_pk_add_f32 v[80:81], v[80:81], v[84:85]
	v_mov_b32_e32 v84, v92
	v_mov_b32_e32 v85, v68
	v_pk_add_f32 v[80:81], v[84:85], v[80:81]
	v_mov_b32_e32 v68, v93
	v_pk_add_f32 v[68:69], v[68:69], v[80:81]
	ds_bpermute_b32 v81, v174, v69
	ds_bpermute_b32 v80, v174, v68
	v_rsq_f32_e32 v0, v0
	s_mov_b32 s0, 0x358637bd
	s_mov_b32 s24, 0x3c800000
	v_lshlrev_b32_e32 v96, 16, v40
	v_mul_f32_e32 v84, 0x45800000, v0
	s_waitcnt lgkmcnt(0)
	v_pk_add_f32 v[80:81], v[68:69], v[80:81]
	v_cndmask_b32_e32 v0, v0, v84, vcc
	ds_bpermute_b32 v85, v175, v81
	ds_bpermute_b32 v84, v175, v80
	v_pk_mul_f32 v[74:75], v[0:1], v[74:75] op_sel_hi:[0,1]
	v_pk_mul_f32 v[78:79], v[0:1], v[78:79] op_sel_hi:[0,1]
	v_pk_mul_f32 v[74:75], v[10:11], v[74:75]
	v_pk_mul_f32 v[78:79], v[8:9], v[78:79]
	v_cvt_pk_bf16_f32 v69, v74, v75
	s_waitcnt lgkmcnt(0)
	v_pk_add_f32 v[74:75], v[80:81], v[84:85]
	v_cvt_pk_bf16_f32 v68, v78, v79
	ds_bpermute_b32 v79, v176, v75
	ds_bpermute_b32 v78, v176, v74
	v_mov_b64_e32 v[84:85], s[0:1]
	v_pk_mul_f32 v[70:71], v[0:1], v[70:71] op_sel_hi:[0,1]
	v_pk_mul_f32 v[2:3], v[0:1], v[2:3] op_sel_hi:[0,1]
	v_pk_mul_f32 v[70:71], v[4:5], v[70:71]
	s_waitcnt lgkmcnt(0)
	v_pk_add_f32 v[74:75], v[74:75], v[78:79]
	v_pk_mul_f32 v[2:3], v[6:7], v[2:3]
	v_pk_fma_f32 v[74:75], v[74:75], s[24:25], v[84:85] op_sel_hi:[1,0,0]
	v_cvt_pk_bf16_f32 v70, v70, v71
	v_mul_f32_e32 v0, 0x4b800000, v75
	v_cmp_gt_f32_e32 vcc, s83, v75
	v_cvt_pk_bf16_f32 v71, v2, v3
	ds_write_b128 v233, v[68:71]
	v_cndmask_b32_e32 v0, v75, v0, vcc
	v_rsq_f32_e32 v0, v0
	v_and_b32_e32 v75, 0xffff0000, v64
	v_lshlrev_b32_e32 v92, 16, v41
	v_and_b32_e32 v93, 0xffff0000, v41
	v_mul_f32_e32 v2, 0x45800000, v0
	v_cndmask_b32_e32 v0, v0, v2, vcc
	v_pk_mul_f32 v[2:3], v[0:1], v[86:87] op_sel_hi:[0,1]
	v_pk_mul_f32 v[2:3], v[8:9], v[2:3]
	v_cmp_gt_f32_e32 vcc, s83, v74
	v_cvt_pk_bf16_f32 v68, v2, v3
	v_pk_mul_f32 v[2:3], v[0:1], v[82:83] op_sel_hi:[0,1]
	v_pk_mul_f32 v[2:3], v[10:11], v[2:3]
	v_and_b32_e32 v97, 0xffff0000, v40
	v_cvt_pk_bf16_f32 v69, v2, v3
	v_pk_mul_f32 v[2:3], v[0:1], v[76:77] op_sel_hi:[0,1]
	v_pk_mul_f32 v[2:3], v[4:5], v[2:3]
	v_lshlrev_b32_e32 v76, 16, v63
	v_cvt_pk_bf16_f32 v70, v2, v3
	v_pk_mul_f32 v[2:3], v[0:1], v[72:73] op_sel_hi:[0,1]
	v_mul_f32_e32 v0, 0x4b800000, v74
	v_cndmask_b32_e32 v0, v74, v0, vcc
	v_rsq_f32_e32 v0, v0
	v_pk_mul_f32 v[2:3], v[6:7], v[2:3]
	v_and_b32_e32 v77, 0xffff0000, v63
	v_cvt_pk_bf16_f32 v71, v2, v3
	v_mul_f32_e32 v2, 0x45800000, v0
	v_cndmask_b32_e32 v0, v0, v2, vcc
	v_pk_mul_f32 v[2:3], v[0:1], v[102:103] op_sel_hi:[0,1]
	v_pk_mul_f32 v[2:3], v[8:9], v[2:3]
	ds_write_b128 v234, v[68:71]
	v_cvt_pk_bf16_f32 v68, v2, v3
	v_pk_mul_f32 v[2:3], v[0:1], v[98:99] op_sel_hi:[0,1]
	v_pk_mul_f32 v[2:3], v[10:11], v[2:3]
	v_lshlrev_b32_e32 v72, 16, v65
	v_cvt_pk_bf16_f32 v69, v2, v3
	v_pk_mul_f32 v[2:3], v[0:1], v[94:95] op_sel_hi:[0,1]
	v_pk_mul_f32 v[2:3], v[4:5], v[2:3]
	v_and_b32_e32 v73, 0xffff0000, v65
	v_cvt_pk_bf16_f32 v70, v2, v3
	v_pk_mul_f32 v[2:3], v[0:1], v[90:91] op_sel_hi:[0,1]
	v_pk_mul_f32 v[2:3], v[6:7], v[2:3]
	v_lshlrev_b32_e32 v74, 16, v64
	v_cvt_pk_bf16_f32 v71, v2, v3
	ds_write_b128 v235, v[68:71]
	v_lshlrev_b32_e32 v68, 16, v67
	v_and_b32_e32 v69, 0xffff0000, v67
	v_lshlrev_b32_e32 v70, 16, v66
	v_and_b32_e32 v71, 0xffff0000, v66
	v_pk_mul_f32 v[78:79], v[68:69], v[68:69]
	v_pk_mul_f32 v[80:81], v[70:71], v[70:71]
	v_pk_fma_f32 v[100:101], v[76:77], v[76:77], v[78:79]
	v_lshlrev_b32_e32 v78, 16, v62
	v_and_b32_e32 v79, 0xffff0000, v62
	v_pk_fma_f32 v[102:103], v[78:79], v[78:79], v[80:81]
	v_lshlrev_b32_e32 v80, 16, v61
	v_and_b32_e32 v81, 0xffff0000, v61
	v_pk_mul_f32 v[82:83], v[72:73], v[72:73]
	v_mul_f32_e32 v0, v96, v96
	v_pk_fma_f32 v[104:105], v[80:81], v[80:81], v[82:83]
	v_lshlrev_b32_e32 v82, 16, v60
	v_and_b32_e32 v83, 0xffff0000, v60
	v_pk_mul_f32 v[106:107], v[74:75], v[74:75]
	v_pk_mul_f32 v[94:95], v[92:93], v[92:93]
	v_pk_fma_f32 v[98:99], v[96:97], v[96:97], v[0:1] op_sel_hi:[1,1,0]
	v_pk_fma_f32 v[106:107], v[82:83], v[82:83], v[106:107]
	v_lshlrev_b32_e32 v88, 16, v42
	v_and_b32_e32 v89, 0xffff0000, v42
	v_mov_b32_e32 v108, v106
	v_mov_b32_e32 v109, v94
	v_mov_b32_e32 v98, v107
	v_pk_mul_f32 v[90:91], v[88:89], v[88:89]
	v_pk_add_f32 v[98:99], v[108:109], v[98:99]
	v_mov_b32_e32 v94, v104
	v_lshlrev_b32_e32 v2, 16, v43
	v_and_b32_e32 v3, 0xffff0000, v43
	v_pk_add_f32 v[94:95], v[94:95], v[98:99]
	v_pk_mov_b32 v[98:99], v[104:105], v[90:91] op_sel:[1,0]
	v_pk_mul_f32 v[86:87], v[2:3], v[2:3]
	v_pk_add_f32 v[94:95], v[98:99], v[94:95]
	v_mov_b32_e32 v90, v102
	v_pk_add_f32 v[90:91], v[90:91], v[94:95]
	v_pk_mov_b32 v[94:95], v[102:103], v[86:87] op_sel:[1,0]
	v_mov_b32_e32 v86, v100
	v_pk_add_f32 v[90:91], v[94:95], v[90:91]
	v_and_b32_e32 v0, 0xffff, v44
	v_pk_add_f32 v[86:87], v[86:87], v[90:91]
	ds_bpermute_b32 v91, v174, v87
	v_mov_b32_e32 v90, v101
	v_lshl_or_b32 v110, v48, 16, v0
	v_lshrrev_b32_e32 v0, 16, v44
	s_mov_b32 s0, 0xffff0000
	s_waitcnt lgkmcnt(0)
	v_pk_add_f32 v[86:87], v[90:91], v[86:87]
	v_and_or_b32 v111, v48, s0, v0
	v_and_b32_e32 v0, 0xffff, v45
	ds_bpermute_b32 v91, v175, v87
	ds_bpermute_b32 v90, v177, v86
	v_lshl_or_b32 v134, v49, 16, v0
	v_lshrrev_b32_e32 v0, 16, v45
	v_and_or_b32 v135, v49, s0, v0
	v_and_b32_e32 v0, 0xffff, v46
	v_lshl_or_b32 v136, v50, 16, v0
	v_lshrrev_b32_e32 v0, 16, v46
	v_and_or_b32 v137, v50, s0, v0
	v_and_b32_e32 v0, 0xffff, v47
	v_lshl_or_b32 v138, v51, 16, v0
	v_lshrrev_b32_e32 v0, 16, v47
	s_waitcnt lgkmcnt(0)
	v_pk_add_f32 v[86:87], v[86:87], v[90:91]
	v_and_or_b32 v139, v51, s0, v0
	v_and_b32_e32 v0, 0xffff, v52
	ds_bpermute_b32 v91, v176, v87
	ds_bpermute_b32 v90, v178, v86
	v_lshl_or_b32 v140, v56, 16, v0
	v_lshrrev_b32_e32 v0, 16, v52
	v_and_or_b32 v94, v56, s0, v0
	v_and_b32_e32 v0, 0xffff, v53
	v_lshl_or_b32 v95, v57, 16, v0
	v_lshrrev_b32_e32 v0, 16, v53
	v_and_or_b32 v98, v57, s0, v0
	v_and_b32_e32 v0, 0xffff, v54
	v_lshl_or_b32 v99, v58, 16, v0
	v_lshrrev_b32_e32 v0, 16, v54
	s_waitcnt lgkmcnt(0)
	v_pk_add_f32 v[86:87], v[86:87], v[90:91]
	v_and_or_b32 v100, v58, s0, v0
	v_and_b32_e32 v0, 0xffff, v55
	v_pk_fma_f32 v[84:85], v[86:87], s[24:25], v[84:85] op_sel_hi:[1,0,0]
	v_lshl_or_b32 v101, v59, 16, v0
	v_mul_f32_e32 v0, 0x4b800000, v85
	v_cmp_gt_f32_e32 vcc, s83, v85
	s_add_i32 s59, s58, s46
	s_cmpk_gt_i32 s59, 0xfff
	v_cndmask_b32_e32 v0, v85, v0, vcc
	v_rsq_f32_e32 v0, v0
	v_lshrrev_b32_e32 v85, 16, v55
	v_and_or_b32 v85, v59, s0, v85
	s_mov_b32 s0, 0x800000
	v_mul_f32_e32 v86, 0x45800000, v0
	v_cndmask_b32_e32 v0, v0, v86, vcc
	v_pk_mul_f32 v[86:87], v[0:1], v[96:97] op_sel_hi:[0,1]
	v_pk_mul_f32 v[90:91], v[0:1], v[92:93] op_sel_hi:[0,1]
	v_pk_mul_f32 v[88:89], v[0:1], v[88:89] op_sel_hi:[0,1]
	v_pk_mul_f32 v[2:3], v[0:1], v[2:3] op_sel_hi:[0,1]
	v_pk_mul_f32 v[86:87], v[8:9], v[86:87]
	v_pk_mul_f32 v[90:91], v[10:11], v[90:91]
	v_pk_mul_f32 v[88:89], v[4:5], v[88:89]
	v_pk_mul_f32 v[2:3], v[6:7], v[2:3]
	v_cvt_pk_bf16_f32 v86, v86, v87
	v_cvt_pk_bf16_f32 v87, v90, v91
	v_cvt_pk_bf16_f32 v88, v88, v89
	v_cvt_pk_bf16_f32 v89, v2, v3
	v_add_u32_e32 v0, 0x9000, v237
	ds_write_b128 v236, v[86:89]
	ds_write2_b32 v0, v110, v111 offset1:132
	v_add_u32_e32 v0, 0x9400, v237
	ds_write2_b32 v0, v134, v135 offset0:8 offset1:140
	v_add_u32_e32 v0, 0x9800, v237
	ds_write2_b32 v0, v136, v137 offset0:16 offset1:148
	v_add_u32_e32 v0, 0x9c00, v237
	ds_write2_b32 v0, v138, v139 offset0:24 offset1:156
	v_add_u32_e32 v0, 0x9000, v238
	ds_write2_b32 v0, v140, v94 offset1:132
	v_add_u32_e32 v0, 0x9400, v238
	ds_write2_b32 v0, v95, v98 offset0:8 offset1:140
	v_add_u32_e32 v0, 0x9800, v238
	s_cselect_b64 s[28:29], -1, 0
	v_cmp_gt_f32_e64 s[82:83], s0, v84
	ds_write2_b32 v0, v99, v100 offset0:16 offset1:148
	v_add_u32_e32 v0, 0x9c00, v238
	s_and_b64 vcc, exec, s[28:29]
	ds_write2_b32 v0, v101, v85 offset0:24 offset1:156
	s_cbranch_vccnz .LBB0_333
	s_and_b32 s0, 0xffff, s47
	s_and_b32 s25, s59, 0x7f
	s_ashr_i32 s24, s59, 11
	s_lshr_b32 s0, s25, s0
	s_and_b32 s25, s25, s56
	s_bfe_u32 s34, s59, 0x40007
	s_lshl_b32 s35, s25, 7
	s_lshl_b32 s25, s24, 4
	s_or_b32 s48, s25, s34
	s_ashr_i32 s49, s48, 31
	s_lshl_b64 s[48:49], s[48:49], 14
	s_lshl_b64 s[52:53], s[0:1], s99
	s_add_u32 s52, s52, s48
	s_addc_u32 s53, s53, s49
	s_add_i32 s25, s35, 0xffffff80
	v_mov_b32_e32 v30, v1
	v_mov_b32_e32 v31, v1
	v_add_u32_e32 v0, s25, v129
	v_mov_b32_e32 v28, v1
	v_mov_b32_e32 v29, v1
	v_mov_b64_e32 v[34:35], v[30:31]
	v_cmp_lt_i32_e32 vcc, -1, v0
	v_mov_b64_e32 v[32:33], v[28:29]
	s_and_saveexec_b64 s[54:55], vcc
	s_cbranch_execz .LBB0_321
	v_lshl_add_u64 v[2:3], s[52:53], 0, v[0:1]
	v_lshlrev_b64 v[2:3], 7, v[2:3]
	v_lshl_add_u64 v[2:3], v[122:123], 0, v[2:3]
	global_load_dwordx4 v[32:35], v[2:3], off
